# loop-edge edit (back-edge rotation) on the P1 GEMM K-loop: counter/pointer updates and next-tile address selects moved from the post-barrier head into the last MFMA block's shadow
# speedup vs baseline: 1.0059x; 1.0059x over previous
.LBB0_148:
	s_ashr_i32 s37, s36, 31
	s_lshl_b64 s[0:1], s[36:37], 20
	s_add_u32 s54, s56, s0
	s_addc_u32 s55, s57, s1
	s_and_b64 s[0:1], s[38:39], exec
	s_cselect_b32 s0, s55, s43
	s_cselect_b32 s1, s54, s42
	s_ashr_i32 s35, s34, 31
	s_lshl_b64 s[12:13], s[34:35], 20
	s_add_u32 s58, s72, s12
	s_addc_u32 s59, s73, s13
	s_and_b64 s[12:13], s[38:39], exec
	s_cselect_b32 s12, s59, s75
	s_cselect_b32 s13, s58, s74
	s_add_u32 s42, s42, 0x80080
	s_addc_u32 s43, s43, 0
	s_add_u32 s14, s74, 0x100
	v_mov_b32_e32 v0, 0
	s_addc_u32 s15, s75, 0
	s_mov_b32 s16, -2
	v_mov_b32_e32 v1, v0
	v_mov_b32_e32 v2, v0
	v_mov_b32_e32 v3, v0
	v_mov_b32_e32 v4, v0
	v_mov_b32_e32 v5, v0
	v_mov_b32_e32 v6, v0
	v_mov_b32_e32 v7, v0
	v_mov_b32_e32 v16, v0
	v_mov_b32_e32 v17, v0
	v_mov_b32_e32 v18, v0
	v_mov_b32_e32 v19, v0
	v_mov_b32_e32 v20, v0
	v_mov_b32_e32 v21, v0
	v_mov_b32_e32 v22, v0
	v_mov_b32_e32 v23, v0
	v_mov_b32_e32 v32, v0
	v_mov_b32_e32 v33, v0
	v_mov_b32_e32 v34, v0
	v_mov_b32_e32 v35, v0
	v_mov_b32_e32 v36, v0
	v_mov_b32_e32 v37, v0
	v_mov_b32_e32 v38, v0
	v_mov_b32_e32 v39, v0
	v_mov_b32_e32 v48, v0
	v_mov_b32_e32 v49, v0
	v_mov_b32_e32 v50, v0
	v_mov_b32_e32 v51, v0
	v_mov_b32_e32 v52, v0
	v_mov_b32_e32 v53, v0
	v_mov_b32_e32 v54, v0
	v_mov_b32_e32 v55, v0
	v_mov_b32_e32 v8, v0
	v_mov_b32_e32 v9, v0
	v_mov_b32_e32 v10, v0
	v_mov_b32_e32 v11, v0
	v_mov_b32_e32 v12, v0
	v_mov_b32_e32 v13, v0
	v_mov_b32_e32 v14, v0
	v_mov_b32_e32 v15, v0
	v_mov_b32_e32 v24, v0
	v_mov_b32_e32 v25, v0
	v_mov_b32_e32 v26, v0
	v_mov_b32_e32 v27, v0
	v_mov_b32_e32 v28, v0
	v_mov_b32_e32 v29, v0
	v_mov_b32_e32 v30, v0
	v_mov_b32_e32 v31, v0
	v_mov_b32_e32 v40, v0
	v_mov_b32_e32 v41, v0
	v_mov_b32_e32 v42, v0
	v_mov_b32_e32 v43, v0
	v_mov_b32_e32 v44, v0
	v_mov_b32_e32 v45, v0
	v_mov_b32_e32 v46, v0
	v_mov_b32_e32 v47, v0
	v_mov_b32_e32 v56, v0
	v_mov_b32_e32 v57, v0
	v_mov_b32_e32 v58, v0
	v_mov_b32_e32 v59, v0
	v_mov_b32_e32 v60, v0
	v_mov_b32_e32 v61, v0
	v_mov_b32_e32 v62, v0
	v_mov_b32_e32 v63, v0
	v_mov_b32_e32 v64, v0
	v_mov_b32_e32 v65, v0
	v_mov_b32_e32 v66, v0
	v_mov_b32_e32 v67, v0
	v_mov_b32_e32 v68, v0
	v_mov_b32_e32 v69, v0
	v_mov_b32_e32 v70, v0
	v_mov_b32_e32 v71, v0
	v_mov_b32_e32 v80, v0
	v_mov_b32_e32 v81, v0
	v_mov_b32_e32 v82, v0
	v_mov_b32_e32 v83, v0
	v_mov_b32_e32 v84, v0
	v_mov_b32_e32 v85, v0
	v_mov_b32_e32 v86, v0
	v_mov_b32_e32 v87, v0
	v_mov_b32_e32 v96, v0
	v_mov_b32_e32 v97, v0
	v_mov_b32_e32 v98, v0
	v_mov_b32_e32 v99, v0
	v_mov_b32_e32 v100, v0
	v_mov_b32_e32 v101, v0
	v_mov_b32_e32 v102, v0
	v_mov_b32_e32 v103, v0
	v_mov_b32_e32 v112, v0
	v_mov_b32_e32 v113, v0
	v_mov_b32_e32 v114, v0
	v_mov_b32_e32 v115, v0
	v_mov_b32_e32 v116, v0
	v_mov_b32_e32 v117, v0
	v_mov_b32_e32 v118, v0
	v_mov_b32_e32 v119, v0
	v_mov_b32_e32 v72, v0
	v_mov_b32_e32 v73, v0
	v_mov_b32_e32 v74, v0
	v_mov_b32_e32 v75, v0
	v_mov_b32_e32 v76, v0
	v_mov_b32_e32 v77, v0
	v_mov_b32_e32 v78, v0
	v_mov_b32_e32 v79, v0
	v_mov_b32_e32 v88, v0
	v_mov_b32_e32 v89, v0
	v_mov_b32_e32 v90, v0
	v_mov_b32_e32 v91, v0
	v_mov_b32_e32 v92, v0
	v_mov_b32_e32 v93, v0
	v_mov_b32_e32 v94, v0
	v_mov_b32_e32 v95, v0
	v_mov_b32_e32 v104, v0
	v_mov_b32_e32 v105, v0
	v_mov_b32_e32 v106, v0
	v_mov_b32_e32 v107, v0
	v_mov_b32_e32 v108, v0
	v_mov_b32_e32 v109, v0
	v_mov_b32_e32 v110, v0
	v_mov_b32_e32 v111, v0
	v_mov_b32_e32 v120, v0
	v_mov_b32_e32 v121, v0
	v_mov_b32_e32 v122, v0
	v_mov_b32_e32 v123, v0
	v_mov_b32_e32 v124, v0
	v_mov_b32_e32 v125, v0
	v_mov_b32_e32 v126, v0
	v_mov_b32_e32 v127, v0
	s_add_u32 s17, s42, 0xfff80080
	s_addc_u32 s19, s43, -1
	s_cmp_eq_u32 s16, 28
	s_cselect_b32 s77, s0, s19
	s_cselect_b32 s76, s1, s17
	s_cselect_b32 s75, s12, s15
	s_cselect_b32 s74, s13, s14
.LBB0_149:
	ds_read_b128 v[128:131], v164
	ds_read_b128 v[150:153], v164 offset:1024
	ds_read_b128 v[154:157], v164 offset:2048
	ds_read_b128 v[158:161], v164 offset:3072
	ds_read_b128 v[170:173], v165
	ds_read_b128 v[174:177], v165 offset:1024
	ds_read_b128 v[178:181], v165 offset:2048
	ds_read_b128 v[182:185], v165 offset:3072
	v_lshl_add_u64 v[218:219], s[42:43], 0, v[142:143]
	s_add_i32 m0, s84, 0xc000
	ds_read_b128 v[186:189], v166
	ds_read_b128 v[190:193], v166 offset:1024
	ds_read_b128 v[194:197], v166 offset:2048
	ds_read_b128 v[198:201], v166 offset:3072
	ds_read_b128 v[202:205], v166 offset:4096
	ds_read_b128 v[206:209], v166 offset:5120
	ds_read_b128 v[210:213], v166 offset:6144
	ds_read_b128 v[214:217], v166 offset:7168
	global_load_lds_dwordx4 v[218:219], off
	v_lshl_add_u64 v[218:219], s[42:43], 0, v[144:145]
	s_add_i32 m0, s84, 0xe000
	s_nop 0
	global_load_lds_dwordx4 v[218:219], off
	s_waitcnt vmcnt(8)
	s_waitcnt lgkmcnt(0)
	s_barrier
	s_setprio 1
	s_waitcnt lgkmcnt(0)
	v_mfma_f32_16x16x32_bf16 v[124:127], v[128:131], v[186:189], v[124:127]
	v_mfma_f32_16x16x32_bf16 v[120:123], v[154:157], v[186:189], v[120:123]
	v_mfma_f32_16x16x32_bf16 v[108:111], v[128:131], v[194:197], v[108:111]
	v_mfma_f32_16x16x32_bf16 v[104:107], v[154:157], v[194:197], v[104:107]
	v_mfma_f32_16x16x32_bf16 v[92:95], v[128:131], v[202:205], v[92:95]
	v_mfma_f32_16x16x32_bf16 v[88:91], v[154:157], v[202:205], v[88:91]
	v_mfma_f32_16x16x32_bf16 v[76:79], v[128:131], v[210:213], v[76:79]
	v_mfma_f32_16x16x32_bf16 v[72:75], v[154:157], v[210:213], v[72:75]
	v_mfma_f32_16x16x32_bf16 v[124:127], v[150:153], v[190:193], v[124:127]
	v_mfma_f32_16x16x32_bf16 v[120:123], v[158:161], v[190:193], v[120:123]
	v_mfma_f32_16x16x32_bf16 v[108:111], v[150:153], v[198:201], v[108:111]
	v_mfma_f32_16x16x32_bf16 v[104:107], v[158:161], v[198:201], v[104:107]
	v_mfma_f32_16x16x32_bf16 v[92:95], v[150:153], v[206:209], v[92:95]
	v_mfma_f32_16x16x32_bf16 v[88:91], v[158:161], v[206:209], v[88:91]
	v_mfma_f32_16x16x32_bf16 v[76:79], v[150:153], v[214:217], v[76:79]
	v_mfma_f32_16x16x32_bf16 v[72:75], v[158:161], v[214:217], v[72:75]
	s_setprio 0
	s_setprio 1
	v_mfma_f32_16x16x32_bf16 v[116:119], v[170:173], v[186:189], v[116:119]
	v_mfma_f32_16x16x32_bf16 v[112:115], v[178:181], v[186:189], v[112:115]
	v_mfma_f32_16x16x32_bf16 v[100:103], v[170:173], v[194:197], v[100:103]
	v_mfma_f32_16x16x32_bf16 v[96:99], v[178:181], v[194:197], v[96:99]
	v_mfma_f32_16x16x32_bf16 v[84:87], v[170:173], v[202:205], v[84:87]
	v_mfma_f32_16x16x32_bf16 v[80:83], v[178:181], v[202:205], v[80:83]
	v_mfma_f32_16x16x32_bf16 v[68:71], v[170:173], v[210:213], v[68:71]
	v_mfma_f32_16x16x32_bf16 v[64:67], v[178:181], v[210:213], v[64:67]
	v_mfma_f32_16x16x32_bf16 v[116:119], v[174:177], v[190:193], v[116:119]
	v_mfma_f32_16x16x32_bf16 v[112:115], v[182:185], v[190:193], v[112:115]
	v_mfma_f32_16x16x32_bf16 v[100:103], v[174:177], v[198:201], v[100:103]
	v_mfma_f32_16x16x32_bf16 v[96:99], v[182:185], v[198:201], v[96:99]
	v_mfma_f32_16x16x32_bf16 v[84:87], v[174:177], v[206:209], v[84:87]
	v_mfma_f32_16x16x32_bf16 v[80:83], v[182:185], v[206:209], v[80:83]
	v_mfma_f32_16x16x32_bf16 v[68:71], v[174:177], v[214:217], v[68:71]
	v_mfma_f32_16x16x32_bf16 v[64:67], v[182:185], v[214:217], v[64:67]
	s_setprio 0
	s_barrier
	s_add_i32 s17, s93, s83
	v_lshl_add_u64 v[218:219], s[74:75], 0, v[134:135]
	s_mov_b32 m0, s17
	ds_read_b128 v[186:189], v166 offset:16384
	ds_read_b128 v[190:193], v166 offset:17408
	ds_read_b128 v[194:197], v166 offset:18432
	ds_read_b128 v[198:201], v166 offset:19456
	ds_read_b128 v[202:205], v166 offset:20480
	ds_read_b128 v[206:209], v166 offset:21504
	ds_read_b128 v[210:213], v166 offset:22528
	ds_read_b128 v[214:217], v166 offset:23552
	global_load_lds_dwordx4 v[218:219], off
	s_add_i32 m0, s17, 0x2000
	s_add_u32 s20, s74, 0x80000
	v_lshl_add_u64 v[220:221], s[74:75], 0, v[138:139]
	s_addc_u32 s21, s75, 0
	s_add_i32 s17, s94, s83
	global_load_lds_dwordx4 v[220:221], off
	v_lshl_add_u64 v[222:223], s[20:21], 0, v[134:135]
	s_mov_b32 m0, s17
	v_lshl_add_u64 v[224:225], s[76:77], 0, v[136:137]
	global_load_lds_dwordx4 v[222:223], off
	v_lshl_add_u64 v[222:223], s[20:21], 0, v[138:139]
	s_add_i32 m0, s17, 0x2000
	s_nop 0
	global_load_lds_dwordx4 v[222:223], off
	v_lshl_add_u64 v[222:223], s[76:77], 0, v[132:133]
	s_mov_b32 m0, s84
	s_nop 0
	global_load_lds_dwordx4 v[222:223], off
	s_mov_b32 m0, s85
	s_nop 0
	global_load_lds_dwordx4 v[224:225], off
	s_waitcnt vmcnt(8)
	s_waitcnt lgkmcnt(0)
	s_barrier
	s_setprio 1
	s_waitcnt lgkmcnt(0)
	v_mfma_f32_16x16x32_bf16 v[60:63], v[128:131], v[186:189], v[60:63]
	v_mfma_f32_16x16x32_bf16 v[56:59], v[154:157], v[186:189], v[56:59]
	v_mfma_f32_16x16x32_bf16 v[44:47], v[128:131], v[194:197], v[44:47]
	v_mfma_f32_16x16x32_bf16 v[40:43], v[154:157], v[194:197], v[40:43]
	v_mfma_f32_16x16x32_bf16 v[28:31], v[128:131], v[202:205], v[28:31]
	v_mfma_f32_16x16x32_bf16 v[24:27], v[154:157], v[202:205], v[24:27]
	v_mfma_f32_16x16x32_bf16 v[12:15], v[128:131], v[210:213], v[12:15]
	v_mfma_f32_16x16x32_bf16 v[8:11], v[154:157], v[210:213], v[8:11]
	v_mfma_f32_16x16x32_bf16 v[60:63], v[150:153], v[190:193], v[60:63]
	v_mfma_f32_16x16x32_bf16 v[56:59], v[158:161], v[190:193], v[56:59]
	v_mfma_f32_16x16x32_bf16 v[44:47], v[150:153], v[198:201], v[44:47]
	v_mfma_f32_16x16x32_bf16 v[40:43], v[158:161], v[198:201], v[40:43]
	v_mfma_f32_16x16x32_bf16 v[28:31], v[150:153], v[206:209], v[28:31]
	v_mfma_f32_16x16x32_bf16 v[24:27], v[158:161], v[206:209], v[24:27]
	v_mfma_f32_16x16x32_bf16 v[12:15], v[150:153], v[214:217], v[12:15]
	v_mfma_f32_16x16x32_bf16 v[8:11], v[158:161], v[214:217], v[8:11]
	s_setprio 0
	s_setprio 1
	v_mfma_f32_16x16x32_bf16 v[52:55], v[170:173], v[186:189], v[52:55]
	v_mfma_f32_16x16x32_bf16 v[48:51], v[178:181], v[186:189], v[48:51]
	v_mfma_f32_16x16x32_bf16 v[36:39], v[170:173], v[194:197], v[36:39]
	v_mfma_f32_16x16x32_bf16 v[32:35], v[178:181], v[194:197], v[32:35]
	v_mfma_f32_16x16x32_bf16 v[20:23], v[170:173], v[202:205], v[20:23]
	v_mfma_f32_16x16x32_bf16 v[16:19], v[178:181], v[202:205], v[16:19]
	v_mfma_f32_16x16x32_bf16 v[4:7], v[170:173], v[210:213], v[4:7]
	v_mfma_f32_16x16x32_bf16 v[0:3], v[178:181], v[210:213], v[0:3]
	v_mfma_f32_16x16x32_bf16 v[52:55], v[174:177], v[190:193], v[52:55]
	v_mfma_f32_16x16x32_bf16 v[48:51], v[182:185], v[190:193], v[48:51]
	v_mfma_f32_16x16x32_bf16 v[36:39], v[174:177], v[198:201], v[36:39]
	v_mfma_f32_16x16x32_bf16 v[32:35], v[182:185], v[198:201], v[32:35]
	v_mfma_f32_16x16x32_bf16 v[20:23], v[174:177], v[206:209], v[20:23]
	v_mfma_f32_16x16x32_bf16 v[16:19], v[182:185], v[206:209], v[16:19]
	v_mfma_f32_16x16x32_bf16 v[4:7], v[174:177], v[214:217], v[4:7]
	v_mfma_f32_16x16x32_bf16 v[0:3], v[182:185], v[214:217], v[0:3]
	s_setprio 0
	s_barrier
	s_add_i32 s17, 0, 0x18000
	v_add_u32_e32 v140, s17, v162
	s_add_i32 s19, 0, 0x1c000
	ds_read_b128 v[128:131], v140
	ds_read_b128 v[150:153], v140 offset:1024
	ds_read_b128 v[154:157], v140 offset:2048
	ds_read_b128 v[158:161], v140 offset:3072
	v_add_u32_e32 v140, s19, v162
	ds_read_b128 v[170:173], v140
	ds_read_b128 v[174:177], v140 offset:1024
	ds_read_b128 v[178:181], v140 offset:2048
	ds_read_b128 v[182:185], v140 offset:3072
	s_add_u32 s20, s76, 0x80000
	s_addc_u32 s21, s77, 0
	s_mov_b32 m0, s86
	v_lshl_add_u64 v[226:227], s[20:21], 0, v[132:133]
	ds_read_b128 v[186:189], v166 offset:32768
	ds_read_b128 v[190:193], v166 offset:33792
	ds_read_b128 v[194:197], v166 offset:34816
	ds_read_b128 v[198:201], v166 offset:35840
	ds_read_b128 v[202:205], v166 offset:36864
	ds_read_b128 v[206:209], v166 offset:37888
	ds_read_b128 v[210:213], v166 offset:38912
	ds_read_b128 v[214:217], v166 offset:39936
	global_load_lds_dwordx4 v[226:227], off
	v_lshl_add_u64 v[226:227], s[20:21], 0, v[136:137]
	s_mov_b32 m0, s87
	s_nop 0
	global_load_lds_dwordx4 v[226:227], off
	s_waitcnt vmcnt(8)
	s_waitcnt lgkmcnt(0)
	s_barrier
	s_setprio 1
	s_waitcnt lgkmcnt(0)
	v_mfma_f32_16x16x32_bf16 v[124:127], v[128:131], v[186:189], v[124:127]
	v_mfma_f32_16x16x32_bf16 v[120:123], v[154:157], v[186:189], v[120:123]
	v_mfma_f32_16x16x32_bf16 v[108:111], v[128:131], v[194:197], v[108:111]
	v_mfma_f32_16x16x32_bf16 v[104:107], v[154:157], v[194:197], v[104:107]
	v_mfma_f32_16x16x32_bf16 v[92:95], v[128:131], v[202:205], v[92:95]
	v_mfma_f32_16x16x32_bf16 v[88:91], v[154:157], v[202:205], v[88:91]
	v_mfma_f32_16x16x32_bf16 v[76:79], v[128:131], v[210:213], v[76:79]
	v_mfma_f32_16x16x32_bf16 v[72:75], v[154:157], v[210:213], v[72:75]
	v_mfma_f32_16x16x32_bf16 v[124:127], v[150:153], v[190:193], v[124:127]
	v_mfma_f32_16x16x32_bf16 v[120:123], v[158:161], v[190:193], v[120:123]
	v_mfma_f32_16x16x32_bf16 v[108:111], v[150:153], v[198:201], v[108:111]
	v_mfma_f32_16x16x32_bf16 v[104:107], v[158:161], v[198:201], v[104:107]
	v_mfma_f32_16x16x32_bf16 v[92:95], v[150:153], v[206:209], v[92:95]
	v_mfma_f32_16x16x32_bf16 v[88:91], v[158:161], v[206:209], v[88:91]
	v_mfma_f32_16x16x32_bf16 v[76:79], v[150:153], v[214:217], v[76:79]
	v_mfma_f32_16x16x32_bf16 v[72:75], v[158:161], v[214:217], v[72:75]
	s_setprio 0
	s_setprio 1
	v_mfma_f32_16x16x32_bf16 v[116:119], v[170:173], v[186:189], v[116:119]
	v_mfma_f32_16x16x32_bf16 v[112:115], v[178:181], v[186:189], v[112:115]
	v_mfma_f32_16x16x32_bf16 v[100:103], v[170:173], v[194:197], v[100:103]
	v_mfma_f32_16x16x32_bf16 v[96:99], v[178:181], v[194:197], v[96:99]
	v_mfma_f32_16x16x32_bf16 v[84:87], v[170:173], v[202:205], v[84:87]
	v_mfma_f32_16x16x32_bf16 v[80:83], v[178:181], v[202:205], v[80:83]
	v_mfma_f32_16x16x32_bf16 v[68:71], v[170:173], v[210:213], v[68:71]
	v_mfma_f32_16x16x32_bf16 v[64:67], v[178:181], v[210:213], v[64:67]
	v_mfma_f32_16x16x32_bf16 v[116:119], v[174:177], v[190:193], v[116:119]
	v_mfma_f32_16x16x32_bf16 v[112:115], v[182:185], v[190:193], v[112:115]
	v_mfma_f32_16x16x32_bf16 v[100:103], v[174:177], v[198:201], v[100:103]
	v_mfma_f32_16x16x32_bf16 v[96:99], v[182:185], v[198:201], v[96:99]
	v_mfma_f32_16x16x32_bf16 v[84:87], v[174:177], v[206:209], v[84:87]
	v_mfma_f32_16x16x32_bf16 v[80:83], v[182:185], v[206:209], v[80:83]
	v_mfma_f32_16x16x32_bf16 v[68:71], v[174:177], v[214:217], v[68:71]
	v_mfma_f32_16x16x32_bf16 v[64:67], v[182:185], v[214:217], v[64:67]
	s_setprio 0
	s_barrier
	s_add_i32 s17, s17, s83
	v_lshl_add_u64 v[218:219], v[218:219], 0, s[10:11]
	s_mov_b32 m0, s17
	ds_read_b128 v[186:189], v166 offset:49152
	ds_read_b128 v[190:193], v166 offset:50176
	ds_read_b128 v[194:197], v166 offset:51200
	ds_read_b128 v[198:201], v166 offset:52224
	ds_read_b128 v[202:205], v166 offset:53248
	ds_read_b128 v[206:209], v166 offset:54272
	ds_read_b128 v[210:213], v166 offset:55296
	ds_read_b128 v[214:217], v166 offset:56320
	global_load_lds_dwordx4 v[218:219], off
	s_add_i32 m0, s17, 0x2000
	s_add_u32 s20, s74, 0x80080
	v_lshl_add_u64 v[218:219], v[220:221], 0, s[10:11]
	s_addc_u32 s21, s75, 0
	s_add_i32 s17, s19, s83
	global_load_lds_dwordx4 v[218:219], off
	v_lshl_add_u64 v[218:219], s[20:21], 0, v[134:135]
	s_mov_b32 m0, s17
	s_nop 0
	global_load_lds_dwordx4 v[218:219], off
	v_lshl_add_u64 v[218:219], s[20:21], 0, v[138:139]
	s_add_i32 m0, s17, 0x2000
	s_nop 0
	global_load_lds_dwordx4 v[218:219], off
	v_lshl_add_u64 v[218:219], v[222:223], 0, s[10:11]
	s_mov_b32 m0, s91
	s_nop 0
	global_load_lds_dwordx4 v[218:219], off
	v_lshl_add_u64 v[218:219], v[224:225], 0, s[10:11]
	s_mov_b32 m0, s92
	s_nop 0
	global_load_lds_dwordx4 v[218:219], off
	s_waitcnt vmcnt(8)
	s_waitcnt lgkmcnt(0)
	s_barrier
	s_setprio 1
	s_waitcnt lgkmcnt(0)
	v_mfma_f32_16x16x32_bf16 v[60:63], v[128:131], v[186:189], v[60:63]
	v_mfma_f32_16x16x32_bf16 v[56:59], v[154:157], v[186:189], v[56:59]
	v_mfma_f32_16x16x32_bf16 v[44:47], v[128:131], v[194:197], v[44:47]
	s_add_i32 s16, s16, 2
	v_mfma_f32_16x16x32_bf16 v[40:43], v[154:157], v[194:197], v[40:43]
	s_add_u32 s42, s42, 0x100
	v_mfma_f32_16x16x32_bf16 v[28:31], v[128:131], v[202:205], v[28:31]
	s_addc_u32 s43, s43, 0
	v_mfma_f32_16x16x32_bf16 v[24:27], v[154:157], v[202:205], v[24:27]
	s_add_u32 s14, s14, 0x100
	v_mfma_f32_16x16x32_bf16 v[12:15], v[128:131], v[210:213], v[12:15]
	s_addc_u32 s15, s15, 0
	v_mfma_f32_16x16x32_bf16 v[8:11], v[154:157], v[210:213], v[8:11]
	s_add_u32 s17, s42, 0xfff80080
	v_mfma_f32_16x16x32_bf16 v[60:63], v[150:153], v[190:193], v[60:63]
	s_addc_u32 s19, s43, -1
	v_mfma_f32_16x16x32_bf16 v[56:59], v[158:161], v[190:193], v[56:59]
	s_cmp_eq_u32 s16, 28
	v_mfma_f32_16x16x32_bf16 v[44:47], v[150:153], v[198:201], v[44:47]
	s_cselect_b32 s77, s0, s19
	v_mfma_f32_16x16x32_bf16 v[40:43], v[158:161], v[198:201], v[40:43]
	s_cselect_b32 s76, s1, s17
	v_mfma_f32_16x16x32_bf16 v[28:31], v[150:153], v[206:209], v[28:31]
	s_cselect_b32 s75, s12, s15
	v_mfma_f32_16x16x32_bf16 v[24:27], v[158:161], v[206:209], v[24:27]
	s_cselect_b32 s74, s13, s14
	v_mfma_f32_16x16x32_bf16 v[12:15], v[150:153], v[214:217], v[12:15]
	s_cmp_gt_u32 s16, 29
	v_mfma_f32_16x16x32_bf16 v[8:11], v[158:161], v[214:217], v[8:11]
	s_setprio 0
	s_setprio 1
	v_mfma_f32_16x16x32_bf16 v[52:55], v[170:173], v[186:189], v[52:55]
	v_mfma_f32_16x16x32_bf16 v[48:51], v[178:181], v[186:189], v[48:51]
	v_mfma_f32_16x16x32_bf16 v[36:39], v[170:173], v[194:197], v[36:39]
	v_mfma_f32_16x16x32_bf16 v[32:35], v[178:181], v[194:197], v[32:35]
	v_mfma_f32_16x16x32_bf16 v[20:23], v[170:173], v[202:205], v[20:23]
	v_mfma_f32_16x16x32_bf16 v[16:19], v[178:181], v[202:205], v[16:19]
	v_mfma_f32_16x16x32_bf16 v[4:7], v[170:173], v[210:213], v[4:7]
	v_mfma_f32_16x16x32_bf16 v[0:3], v[178:181], v[210:213], v[0:3]
	v_mfma_f32_16x16x32_bf16 v[52:55], v[174:177], v[190:193], v[52:55]
	v_mfma_f32_16x16x32_bf16 v[48:51], v[182:185], v[190:193], v[48:51]
	v_mfma_f32_16x16x32_bf16 v[36:39], v[174:177], v[198:201], v[36:39]
	v_mfma_f32_16x16x32_bf16 v[32:35], v[182:185], v[198:201], v[32:35]
	v_mfma_f32_16x16x32_bf16 v[20:23], v[174:177], v[206:209], v[20:23]
	v_mfma_f32_16x16x32_bf16 v[16:19], v[182:185], v[206:209], v[16:19]
	v_mfma_f32_16x16x32_bf16 v[4:7], v[174:177], v[214:217], v[4:7]
	v_mfma_f32_16x16x32_bf16 v[0:3], v[182:185], v[214:217], v[0:3]
	s_setprio 0
	s_barrier
	s_cbranch_scc0 .LBB0_149
	s_and_b64 vcc, exec, s[30:31]
	s_cbranch_vccz .LBB0_152
	s_barrier
